# out-proj GEMM: half of the workgroups start ~13us later so the HBM-bound residual epilogues interleave with the other half's MFMA loops
# baseline (speedup 1.0000x reference)
.LBB0_829:
	s_or_b64 exec, exec, s[4:5]
	s_mov_b32 s3, s33
	s_waitcnt lgkmcnt(0)
	s_barrier
	v_mbcnt_lo_u32_b32 v10, -1, 0
	v_mbcnt_hi_u32_b32 v10, -1, v10
	s_and_b64 vcc, exec, s[0:1]
	v_lshl_or_b32 v0, s3, 6, v10
	s_nop 0
	v_readfirstlane_b32 s0, v0
	s_cbranch_vccnz .LBB0_213
	s_and_b32 s4, s28, 8
	s_cmp_eq_u32 s4, 0
	s_cbranch_scc1 .Lstag_out_skip
	s_sleep 127
	s_sleep 127
	s_sleep 127
.Lstag_out_skip:
	v_lshlrev_b32_e32 v1, 4, v0
	v_add_u32_e32 v2, 0x2000, v1
	v_ashrrev_i32_e32 v3, 31, v2
	v_lshrrev_b32_e32 v3, 22, v3
	v_add_u32_e32 v3, v2, v3
	v_ashrrev_i32_e32 v4, 10, v3
	v_mul_i32_i24_e32 v5, 0x400, v4
	v_sub_u32_e32 v2, v2, v5
	v_lshrrev_b32_e32 v5, 4, v2
	v_bitop3_b32 v2, v5, v2, 32 bitop3:0x6c
	v_ashrrev_i32_e32 v5, 31, v2
	v_lshrrev_b32_e32 v5, 26, v5
	v_add_u32_e32 v6, v2, v5
	v_ashrrev_i32_e32 v5, 6, v6
	v_and_b32_e32 v6, 0xc0, v6
	v_sub_u32_e32 v2, v2, v6
	v_mov_b32_e32 v9, 1
	v_lshlrev_b32_e32 v3, 5, v4
	v_ashrrev_i16_sdwa v2, v9, sext(v2) dst_sel:DWORD dst_unused:UNUSED_PAD src0_sel:DWORD src1_sel:BYTE_0
	v_and_b32_e32 v3, 32, v3
	v_bfe_i32 v6, v2, 0, 16
	v_add_u32_e32 v2, v3, v6
	v_lshlrev_b32_e32 v3, 3, v4
	v_and_b32_e32 v3, 0x1ffff0, v3
	v_add_lshl_u32 v3, v5, v3, 11
	v_lshl_add_u32 v178, v2, 1, v3
	v_ashrrev_i32_e32 v2, 31, v0
	v_lshrrev_b32_e32 v2, 26, v2
	v_add_u32_e32 v2, v0, v2
	v_bfe_i32 v0, v0, 27, 1
	v_lshrrev_b32_e32 v0, 22, v0
	v_add_u32_e32 v0, v1, v0
	v_and_b32_e32 v0, 0xfffffc00, v0
	v_sub_u32_e32 v0, v1, v0
	v_lshrrev_b32_e32 v1, 4, v0
	v_bitop3_b32 v0, v1, v0, 32 bitop3:0x6c
	v_readlane_b32 s4, v254, 53
	v_ashrrev_i32_e32 v1, 31, v0
	v_readlane_b32 s5, v254, 54
	v_lshrrev_b32_e32 v1, 26, v1
	s_lshl_b64 s[4:5], s[4:5], 21
	v_readlane_b32 s1, v253, 0
	v_add_u32_e32 v1, v0, v1
	s_add_u32 s3, s1, s4
	v_readlane_b32 s1, v253, 1
	v_ashrrev_i32_e32 v8, 6, v1
	v_and_b32_e32 v1, 0xc0, v1
	s_addc_u32 s25, s1, s5
	s_ashr_i32 s1, s0, 6
	v_ashrrev_i32_e32 v7, 6, v2
	v_sub_u32_e32 v0, v0, v1
	s_ashr_i32 s6, s0, 8
	s_lshl_b32 s34, s1, 10
	v_lshlrev_b32_e32 v2, 5, v7
	v_ashrrev_i16_sdwa v0, v9, sext(v0) dst_sel:DWORD dst_unused:UNUSED_PAD src0_sel:DWORD src1_sel:BYTE_0
	v_lshlrev_b32_e32 v1, 3, v7
	v_readlane_b32 s4, v254, 11
	v_and_b32_e32 v2, 32, v2
	v_bfe_i32 v9, v0, 0, 16
	v_and_b32_e32 v1, 0x1ffff0, v1
	v_readlane_b32 s5, v254, 12
	s_add_u32 s54, s3, s4
	v_add_u32_e32 v0, v2, v9
	v_add_lshl_u32 v1, v8, v1, 11
	s_addc_u32 s55, s25, s5
	s_add_i32 s35, s34, 0
	v_lshl_add_u32 v12, v0, 1, v1
	s_add_i32 m0, s35, 0x10000
	v_mov_b32_e32 v179, v13
	global_load_lds_dwordx4 v12, s[54:55]
	s_add_i32 m0, s35, 0x12000
	s_add_u32 s4, s54, 0x40000
	global_load_lds_dwordx4 v178, s[54:55]
	s_addc_u32 s5, s55, 0
	s_add_i32 m0, s35, 0x14000
	s_add_i32 s38, s35, 0x2000
	global_load_lds_dwordx4 v12, s[4:5]
	s_add_i32 m0, s35, 0x16000
	s_add_i32 s39, s35, 0x4000
	global_load_lds_dwordx4 v178, s[4:5]
	v_readlane_b32 s4, v254, 15
	s_mov_b32 m0, s35
	v_readlane_b32 s5, v254, 16
	s_add_i32 s40, s35, 0x6000
	s_cmp_eq_u32 s6, 1
	v_lshl_add_u64 v[0:1], s[54:55], 0, v[12:13]
	v_lshl_add_u64 v[2:3], s[54:55], 0, v[178:179]
	s_nop 0
	global_load_lds_dwordx4 v12, s[4:5]
	s_mov_b32 m0, s38
	s_nop 0
	global_load_lds_dwordx4 v178, s[4:5]
	v_readlane_b32 s4, v254, 17
	s_mov_b32 m0, s39
	v_readlane_b32 s5, v254, 18
	s_nop 4
	global_load_lds_dwordx4 v12, s[4:5]
	s_mov_b32 m0, s40
	s_nop 0
	global_load_lds_dwordx4 v178, s[4:5]
	s_cselect_b64 s[4:5], -1, 0
	s_cmp_lg_u32 s6, 1
	s_cbranch_scc1 .LBB0_832
	s_barrier
